# v81: lever 4 - one static s_setprio 1 for waves 4-7 across the attention phase (reset at its exit)
# baseline (speedup 1.0000x reference)
.LBB0_561:
	s_cmp_ge_i32 s8, s68
	s_cselect_b64 s[0:1], -1, 0
	s_and_b64 s[62:63], s[0:1], s[10:11]
	s_andn2_b64 vcc, exec, s[62:63]
	s_cbranch_vccnz .LBB0_615
	v_readlane_b32 s0, v253, 8
	v_mov_b32_e32 v0, v222
	v_readlane_b32 s1, v253, 9
	s_andn2_b64 vcc, exec, s[0:1]
	v_readfirstlane_b32 s0, v0
	s_cbranch_vccnz .LBB0_611
	v_cmp_lt_i32_e32 vcc, v206, v205
	v_and_b32_e32 v2, 7, v0
	v_lshlrev_b32_e32 v86, 3, v2
	v_cndmask_b32_e32 v3, v204, v206, vcc
	v_lshlrev_b32_e32 v113, 2, v3
	v_cmp_gt_u32_e64 s[46:47], 2, v2
	v_lshl_add_u32 v3, v2, 4, 0
	v_cmp_eq_u32_e32 vcc, 0, v2
	v_xor_b32_e32 v2, 16, v204
	v_and_b32_e32 v87, 15, v0
	s_ashr_i32 s20, s0, 7
	s_and_b32 s21, s0, 64
	v_cndmask_b32_e64 v88, 1.0, -1.0, vcc
	v_cmp_lt_i32_e32 vcc, v2, v205
	s_movk_i32 s0, 0x310
	v_mad_u32_u24 v118, v87, s0, 0
	v_cndmask_b32_e32 v2, v204, v2, vcc
	s_mov_b32 s0, 0x2aaaaaab
	v_lshlrev_b32_e32 v114, 2, v2
	v_lshlrev_b32_e32 v2, 1, v0
	v_and_b32_e32 v4, 3, v0
	v_mul_hi_i32 v13, v0, s0
	v_and_or_b32 v115, v2, 24, v4
	v_xor_b32_e32 v2, 32, v204
	v_lshrrev_b32_e32 v14, 31, v13
	v_ashrrev_i32_e32 v13, 6, v13
	v_cmp_lt_i32_e32 vcc, v2, v205
	v_add_u32_e32 v13, v13, v14
	s_movk_i32 s1, 0xfe80
	v_cndmask_b32_e32 v2, v204, v2, vcc
	v_mad_i32_i24 v125, v13, s1, v0
	v_lshlrev_b32_e32 v117, 2, v2
	v_add_u32_e32 v2, 0x200, v0
	v_lshlrev_b32_e32 v92, 3, v13
	v_mul_i32_i24_e32 v13, 0x1880, v13
	v_lshlrev_b32_e32 v14, 1, v125
	v_add3_u32 v126, 0, v13, v14
	v_mul_hi_i32 v13, v2, s0
	v_lshrrev_b32_e32 v14, 31, v13
	v_ashrrev_i32_e32 v13, 6, v13
	v_add_u32_e32 v13, v13, v14
	v_mul_i32_i24_e32 v14, 0xfffffe80, v13
	v_ashrrev_i32_e32 v120, 3, v2
	v_add_u32_e32 v5, 0x400, v0
	v_mad_i32_i24 v127, v13, s1, v2
	v_lshlrev_b32_e32 v94, 3, v13
	v_mul_i32_i24_e32 v2, 0x1880, v13
	v_add_lshl_u32 v13, v14, v0, 1
	v_add3_u32 v128, 0, v2, v13
	v_mul_hi_i32 v2, v5, s0
	v_lshrrev_b32_e32 v13, 31, v2
	v_ashrrev_i32_e32 v2, 6, v2
	v_add_u32_e32 v2, v2, v13
	v_mul_i32_i24_e32 v13, 0xfffffe80, v2
	v_ashrrev_i32_e32 v121, 3, v5
	v_add_u32_e32 v7, 0x600, v0
	v_mad_i32_i24 v129, v2, s1, v5
	v_lshlrev_b32_e32 v96, 3, v2
	v_mul_i32_i24_e32 v2, 0x1880, v2
	v_add_lshl_u32 v5, v13, v0, 1
	v_add3_u32 v130, 0, v2, v5
	v_mul_hi_i32 v2, v7, s0
	v_lshrrev_b32_e32 v5, 31, v2
	v_ashrrev_i32_e32 v2, 6, v2
	v_add_u32_e32 v2, v2, v5
	v_mul_i32_i24_e32 v5, 0xfffffe80, v2
	v_add_u32_e32 v9, 0x800, v0
	s_waitcnt lgkmcnt(0)
	v_mad_i32_i24 v131, v2, s1, v7
	v_lshlrev_b32_e32 v98, 3, v2
	v_mul_i32_i24_e32 v2, 0x1880, v2
	v_add_lshl_u32 v5, v5, v0, 1
	v_add3_u32 v132, 0, v2, v5
	v_mul_hi_i32 v2, v9, s0
	v_lshrrev_b32_e32 v5, 31, v2
	v_ashrrev_i32_e32 v2, 6, v2
	v_add_u32_e32 v2, v2, v5
	v_mul_i32_i24_e32 v5, 0xfffffe80, v2
	v_add_u32_e32 v11, 0xa00, v0
	v_mad_i32_i24 v133, v2, s1, v9
	v_lshlrev_b32_e32 v100, 3, v2
	v_mul_i32_i24_e32 v2, 0x1880, v2
	v_add_lshl_u32 v5, v5, v0, 1
	v_add3_u32 v134, 0, v2, v5
	v_mul_hi_i32 v2, v11, s0
	v_lshrrev_b32_e32 v5, 31, v2
	v_ashrrev_i32_e32 v2, 6, v2
	v_add_u32_e32 v2, v2, v5
	v_bfe_u32 v1, v0, 4, 2
	v_mul_i32_i24_e32 v5, 0xfffffe80, v2
	v_cmp_eq_u32_e32 vcc, 0, v1
	v_ashrrev_i32_e32 v119, 3, v0
	v_ashrrev_i32_e32 v122, 3, v7
	v_ashrrev_i32_e32 v123, 3, v9
	v_ashrrev_i32_e32 v124, 3, v11
	v_mad_i32_i24 v135, v2, s1, v11
	v_lshlrev_b32_e32 v102, 3, v2
	v_mul_i32_i24_e32 v2, 0x1880, v2
	v_add_lshl_u32 v0, v5, v0, 1
	v_lshlrev_b32_e32 v84, 3, v1
	v_mov_b32_e32 v85, v153
	v_cmp_gt_u32_e64 s[48:49], 2, v1
	v_lshl_add_u32 v116, v1, 4, 0
	v_cndmask_b32_e64 v90, 1.0, -1.0, vcc
	v_mul_lo_u32 v1, v119, s25
	v_mul_lo_u32 v4, v120, s25
	v_mul_lo_u32 v6, v121, s25
	v_mul_lo_u32 v8, v122, s25
	v_mul_lo_u32 v10, v123, s25
	v_mul_lo_u32 v12, v124, s25
	v_add3_u32 v136, 0, v2, v0
	v_readlane_b32 s10, v253, 43
	v_or_b32_e32 v112, s21, v87
	v_ashrrev_i32_e32 v93, 31, v92
	v_ashrrev_i32_e32 v95, 31, v94
	v_ashrrev_i32_e32 v97, 31, v96
	v_ashrrev_i32_e32 v99, 31, v98
	v_ashrrev_i32_e32 v101, 31, v100
	v_ashrrev_i32_e32 v103, 31, v102
	v_add_u32_e32 v137, 0xec00, v136
	v_mov_b32_e32 v89, v88
	v_mov_b32_e32 v91, v90
	v_lshl_add_u64 v[104:105], s[34:35], 0, v[84:85]
	s_lshl_b32 s44, s20, 6
	v_add_u32_e32 v85, v3, v1
	v_add_u32_e32 v138, v3, v4
	v_add_u32_e32 v139, v3, v6
	v_add_u32_e32 v140, v3, v8
	v_add_u32_e32 v141, v3, v10
	v_add_u32_e32 v142, v3, v12
	v_readlane_b32 s11, v253, 44
	v_readlane_b32 s45, v253, 42
	v_readfirstlane_b32 s32, v222
	s_nop 3
	s_cmp_ge_u32 s32, 0x100
	s_cbranch_scc0 .Lmy_attn_prio
	s_setprio 1
.Lmy_attn_prio:
	s_branch .LBB0_565

.LBB0_611:
	s_setprio 0
	v_readlane_b32 s0, v253, 13
	v_readlane_b32 s1, v253, 14
	v_readlane_b32 s60, v253, 55
	s_andn2_b64 vcc, exec, s[0:1]
	v_readlane_b32 s0, v253, 48
	v_readlane_b32 s8, v253, 47
	v_readlane_b32 s61, v253, 56
	s_waitcnt vmcnt(0) lgkmcnt(0)
	s_barrier
	s_cbranch_vccnz .LBB0_615
